# attention: V-fragment LDS base address (2 SALU + 1 VALU) computed at the end of the load phase instead of at the head of the compute phase, so the compute segment opens with MFMAs only
# speedup vs baseline: 1.0127x; 1.0127x over previous
; DI unsigned pack2(float a, float b) { f32x2_t v = {a, b}; bf16x2_t r = __builtin_convertvector(v, bf16x2_t); return __builtin_bit_cast(unsigned, r); }
; #define LOADT(key0) do { kr0 = *(const uint4*)(Kp + (size_t)((key0) + krow0) * ldk + kch0 * 8); \
;     if (k2) kr1 = *(const uint4*)(Kp + (size_t)((key0) + krow1) * ldk + kch1 * 8); \
;     vr = *(const uint4*)(Vt + (size_t)vrow * S_ + (key0) + vch * 8); } while (0)
; #define STORET(bufi) do { char* bb = smem + (bufi) * BUF; *(uint4*)(bb + krow0 * KS + kch0 * 16) = kr0; \
;     if (k2) *(uint4*)(bb + krow1 * KS + kch1 * 16) = kr1; \
;     *(uint4*)(bb + KB + vrow * VS + vch * 16) = vr; } while (0)
; #define BARX do { __builtin_amdgcn_sched_barrier(0); asm volatile("s_waitcnt lgkmcnt(0)" ::: "memory"); __builtin_amdgcn_s_barrier(); __builtin_amdgcn_sched_barrier(0); } while (0)
; template <int D>
; DI void attn_tile(const u16* __restrict__ Qp, int ldq, const u16* __restrict__ Kp, int ldk, const u16* __restrict__ Vt,
;                   u16* __restrict__ Op, int ldo, int q0, float cs, float mc) {
;     ...
;     bf16x8 pf[2][2];
;     if (mc != 0.f) {
; #pragma unroll
;       for (int i = 0; i < 16; ++i) { s0[i] -= mc; s1[i] -= mc; }
;     }
; #pragma unroll
;     for (int i = 0; i < 16; ++i) {
;       s0[i] = __builtin_amdgcn_exp2f(s0[i]); s1[i] = __builtin_amdgcn_exp2f(s1[i]);
;       lsum0 += s0[i]; lsum1 += s1[i];
;     }
; #pragma unroll
;     for (int st = 0; st < 2; ++st) {
;       uint4 a = {pack2(s0[8 * st], s0[8 * st + 1]), pack2(s0[8 * st + 2], s0[8 * st + 3]), pack2(s0[8 * st + 4], s0[8 * st + 5]), pack2(s0[8 * st + 6], s0[8 * st + 7])};
;       uint4 c = {pack2(s1[8 * st], s1[8 * st + 1]), pack2(s1[8 * st + 2], s1[8 * st + 3]), pack2(s1[8 * st + 4], s1[8 * st + 5]), pack2(s1[8 * st + 6], s1[8 * st + 7])};
;       pf[0][st] = __builtin_bit_cast(bf16x8, a); pf[1][st] = __builtin_bit_cast(bf16x8, c);
;     }
;     if (it + 2 < NIT) STORET((it + 2) & 3);
;     if (it + 3 < NIT) LOADT((it + 3) * 64);
;     if (it + 1 < NIT) LOADKF((it + 1) & 3);
;     BARX;
;     __builtin_amdgcn_s_setprio(1);
;     {
;       const char* vb = smem + (it & 3) * BUF + KB + r * VS + 16 * hh;
;       bf16x8 v0[2], v1[2];
; #pragma unroll
;       for (int q = 0; q < 2; ++q) { v0[q] = *(const bf16x8*)(vb + 32 * q); v1[q] = *(const bf16x8*)(vb + 32 * VS + 32 * q); }
;       if (it + 1 < NIT) SMMA();
.LBB0_198:
	s_and_b32 s44, s36, 3
	s_mulk_i32 s44, 0x5800
	v_add_u32_e32 v226, s44, v249
	ds_read_b128 v[128:131], v226
	ds_read_b128 v[132:135], v226 offset:32
	ds_read_b128 v[140:143], v226 offset:6656
	ds_read_b128 v[144:147], v226 offset:6688
	ds_read_b128 v[148:151], v226 offset:64
	ds_read_b128 v[152:155], v226 offset:96
	ds_read_b128 v[156:159], v226 offset:6720
	ds_read_b128 v[160:163], v226 offset:6752
	ds_read_b128 v[164:167], v226 offset:128
	ds_read_b128 v[168:171], v226 offset:160
	ds_read_b128 v[172:175], v226 offset:6784
	ds_read_b128 v[176:179], v226 offset:6816
	s_and_b32 s10, s37, 3
	s_mulk_i32 s10, 0x5800
	v_add_u32_e32 v201, s10, v196
	s_waitcnt lgkmcnt(0)
	s_barrier
	s_setprio 1
	v_mfma_f32_32x32x16_bf16 v[32:47], v[128:131], v[96:99], 0
	ds_read_b128 v[188:191], v201 offset:13312
	ds_read_b128 v[192:195], v201 offset:17920
	v_cvt_pk_bf16_f32 v210, v64, v65
	v_cvt_pk_bf16_f32 v211, v66, v67
	v_cvt_pk_bf16_f32 v212, v68, v69
	v_cvt_pk_bf16_f32 v213, v70, v71
	v_mfma_f32_32x32x16_bf16 v[48:63], v[140:143], v[96:99], 0
	ds_read_b128 v[184:187], v201 offset:13344
	ds_read_b128 v[180:183], v201 offset:17952
	v_cvt_pk_bf16_f32 v214, v72, v73
	v_cvt_pk_bf16_f32 v215, v74, v75
	v_cvt_pk_bf16_f32 v216, v76, v77
	v_cvt_pk_bf16_f32 v217, v78, v79
	v_mfma_f32_32x32x16_bf16 v[32:47], v[132:135], v[100:103], v[32:47]
	v_cvt_pk_bf16_f32 v218, v80, v81
	v_cvt_pk_bf16_f32 v219, v82, v83
	v_cvt_pk_bf16_f32 v220, v84, v85
	v_cvt_pk_bf16_f32 v221, v86, v87
	v_mfma_f32_32x32x16_bf16 v[48:63], v[144:147], v[100:103], v[48:63]
	v_cvt_pk_bf16_f32 v222, v88, v89
	v_cvt_pk_bf16_f32 v223, v90, v91
	v_cvt_pk_bf16_f32 v224, v92, v93
	v_cvt_pk_bf16_f32 v225, v94, v95
	v_mfma_f32_32x32x16_bf16 v[32:47], v[148:151], v[104:107], v[32:47]
	v_add_f32_e32 v208, v64, v208
	v_add_f32_e32 v209, v80, v209
	v_add_f32_e32 v208, v65, v208
	v_add_f32_e32 v209, v81, v209
	v_mfma_f32_32x32x16_bf16 v[48:63], v[156:159], v[104:107], v[48:63]
	v_add_f32_e32 v208, v66, v208
	v_add_f32_e32 v209, v82, v209
	v_add_f32_e32 v208, v67, v208
	v_add_f32_e32 v209, v83, v209
	v_mfma_f32_32x32x16_bf16 v[32:47], v[152:155], v[108:111], v[32:47]
	v_add_f32_e32 v208, v68, v208
	v_add_f32_e32 v209, v84, v209
	v_add_f32_e32 v208, v69, v208
	v_add_f32_e32 v209, v85, v209
	v_mfma_f32_32x32x16_bf16 v[48:63], v[160:163], v[108:111], v[48:63]
	v_add_f32_e32 v208, v70, v208
	v_add_f32_e32 v209, v86, v209
	v_add_f32_e32 v208, v71, v208
	v_add_f32_e32 v209, v87, v209
	v_mfma_f32_32x32x16_bf16 v[32:47], v[164:167], v[112:115], v[32:47]
	v_add_f32_e32 v208, v72, v208
	v_add_f32_e32 v209, v88, v209
	v_add_f32_e32 v208, v73, v208
	v_add_f32_e32 v209, v89, v209
	v_mfma_f32_32x32x16_bf16 v[48:63], v[172:175], v[112:115], v[48:63]
	v_add_f32_e32 v208, v74, v208
	v_add_f32_e32 v209, v90, v209
	v_add_f32_e32 v208, v75, v208
	v_add_f32_e32 v209, v91, v209
	v_mfma_f32_32x32x16_bf16 v[32:47], v[168:171], v[116:119], v[32:47]
	v_add_f32_e32 v208, v76, v208
	v_add_f32_e32 v209, v92, v209
	v_add_f32_e32 v208, v77, v208
	v_add_f32_e32 v209, v93, v209
	v_mfma_f32_32x32x16_bf16 v[48:63], v[176:179], v[116:119], v[48:63]
	v_add_f32_e32 v208, v78, v208
	v_add_f32_e32 v209, v94, v209
	v_add_f32_e32 v208, v79, v208
	v_add_f32_e32 v209, v95, v209
	ds_read_b128 v[140:143], v201 offset:13376
	ds_read_b128 v[144:147], v201 offset:17984
	ds_read_b128 v[148:151], v201 offset:13408
	ds_read_b128 v[152:155], v201 offset:18016
	s_andn2_b64 vcc, exec, s[38:39]
	s_cbranch_vccnz .LBB0_190
	s_nop 3
	v_sub_f32_e32 v47, v47, v232
	v_sub_f32_e32 v46, v46, v232
	v_sub_f32_e32 v45, v45, v232
	v_sub_f32_e32 v44, v44, v232
	v_sub_f32_e32 v43, v43, v232
	v_sub_f32_e32 v42, v42, v232
	v_sub_f32_e32 v41, v41, v232
	v_sub_f32_e32 v40, v40, v232
	v_sub_f32_e32 v39, v39, v232
	v_sub_f32_e32 v38, v38, v232
	v_sub_f32_e32 v37, v37, v232
	v_sub_f32_e32 v36, v36, v232
	v_sub_f32_e32 v35, v35, v232
	v_sub_f32_e32 v34, v34, v232
	v_sub_f32_e32 v33, v33, v232
	v_sub_f32_e32 v32, v32, v232
	v_sub_f32_e32 v63, v63, v232
	v_sub_f32_e32 v62, v62, v232
	v_sub_f32_e32 v61, v61, v232
	v_sub_f32_e32 v60, v60, v232
	v_sub_f32_e32 v59, v59, v232
	v_sub_f32_e32 v58, v58, v232
	v_sub_f32_e32 v57, v57, v232
	v_sub_f32_e32 v56, v56, v232
	v_sub_f32_e32 v55, v55, v232
	v_sub_f32_e32 v54, v54, v232
	v_sub_f32_e32 v53, v53, v232
	v_sub_f32_e32 v52, v52, v232
	v_sub_f32_e32 v51, v51, v232
	v_sub_f32_e32 v50, v50, v232
	v_sub_f32_e32 v49, v49, v232
	v_sub_f32_e32 v48, v48, v232

; DI unsigned pack2(float a, float b) { f32x2_t v = {a, b}; bf16x2_t r = __builtin_convertvector(v, bf16x2_t); return __builtin_bit_cast(unsigned, r); }
; #define LOADT(key0) do { kr0 = *(const uint4*)(Kp + (size_t)((key0) + krow0) * ldk + kch0 * 8); \
;     if (k2) kr1 = *(const uint4*)(Kp + (size_t)((key0) + krow1) * ldk + kch1 * 8); \
;     vr = *(const uint4*)(Vt + (size_t)vrow * S_ + (key0) + vch * 8); } while (0)
; #define STORET(bufi) do { char* bb = smem + (bufi) * BUF; *(uint4*)(bb + krow0 * KS + kch0 * 16) = kr0; \
;     if (k2) *(uint4*)(bb + krow1 * KS + kch1 * 16) = kr1; \
;     *(uint4*)(bb + KB + vrow * VS + vch * 16) = vr; } while (0)
; #define BARX do { __builtin_amdgcn_sched_barrier(0); asm volatile("s_waitcnt lgkmcnt(0)" ::: "memory"); __builtin_amdgcn_s_barrier(); __builtin_amdgcn_sched_barrier(0); } while (0)
; template <int D>
; DI void attn_tile(const u16* __restrict__ Qp, int ldq, const u16* __restrict__ Kp, int ldk, const u16* __restrict__ Vt,
;                   u16* __restrict__ Op, int ldo, int q0, float cs, float mc) {
;     ...
;     bf16x8 pf[2][2];
;     if (mc != 0.f) {
; #pragma unroll
;       for (int i = 0; i < 16; ++i) { s0[i] -= mc; s1[i] -= mc; }
;     }
; #pragma unroll
;     for (int i = 0; i < 16; ++i) {
;       s0[i] = __builtin_amdgcn_exp2f(s0[i]); s1[i] = __builtin_amdgcn_exp2f(s1[i]);
;       lsum0 += s0[i]; lsum1 += s1[i];
;     }
; #pragma unroll
;     for (int st = 0; st < 2; ++st) {
;       uint4 a = {pack2(s0[8 * st], s0[8 * st + 1]), pack2(s0[8 * st + 2], s0[8 * st + 3]), pack2(s0[8 * st + 4], s0[8 * st + 5]), pack2(s0[8 * st + 6], s0[8 * st + 7])};
;       uint4 c = {pack2(s1[8 * st], s1[8 * st + 1]), pack2(s1[8 * st + 2], s1[8 * st + 3]), pack2(s1[8 * st + 4], s1[8 * st + 5]), pack2(s1[8 * st + 6], s1[8 * st + 7])};
;       pf[0][st] = __builtin_bit_cast(bf16x8, a); pf[1][st] = __builtin_bit_cast(bf16x8, c);
;     }
;     if (it + 2 < NIT) STORET((it + 2) & 3);
;     if (it + 3 < NIT) LOADT((it + 3) * 64);
;     if (it + 1 < NIT) LOADKF((it + 1) & 3);
;     BARX;
;     __builtin_amdgcn_s_setprio(1);
;     {
;       const char* vb = smem + (it & 3) * BUF + KB + r * VS + 16 * hh;
;       bf16x8 v0[2], v1[2];
; #pragma unroll
;       for (int q = 0; q < 2; ++q) { v0[q] = *(const bf16x8*)(vb + 32 * q); v1[q] = *(const bf16x8*)(vb + 32 * VS + 32 * q); }
;       if (it + 1 < NIT) SMMA();
.LBB0_836:
	s_and_b32 s40, s36, 3
	s_mulk_i32 s40, 0x4800
	v_add_u32_e32 v192, s40, v204
	ds_read_b128 v[120:123], v192
	ds_read_b128 v[124:127], v192 offset:32
	ds_read_b128 v[128:131], v192 offset:4608
	ds_read_b128 v[132:135], v192 offset:4640
	ds_read_b128 v[136:139], v192 offset:64
	ds_read_b128 v[140:143], v192 offset:96
	ds_read_b128 v[144:147], v192 offset:4672
	ds_read_b128 v[148:151], v192 offset:4704
	s_and_b32 s10, s37, 3
	s_mulk_i32 s10, 0x4800
	v_add_u32_e32 v196, s10, v204
	s_waitcnt lgkmcnt(0)
	s_barrier
	s_setprio 1
	v_mfma_f32_32x32x16_bf16 v[32:47], v[120:123], v[96:99], 0
	ds_read_b128 v[152:155], v196 offset:9216
	ds_read_b128 v[160:163], v196 offset:13824
	v_cvt_pk_bf16_f32 v176, v64, v65
	v_cvt_pk_bf16_f32 v177, v66, v67
	v_cvt_pk_bf16_f32 v178, v68, v69
	v_cvt_pk_bf16_f32 v179, v70, v71
	v_add_f32_e32 v174, v64, v174
	v_add_f32_e32 v175, v80, v175
	v_mfma_f32_32x32x16_bf16 v[48:63], v[128:131], v[96:99], 0
	ds_read_b128 v[156:159], v196 offset:9248
	ds_read_b128 v[164:167], v196 offset:13856
	v_cvt_pk_bf16_f32 v180, v72, v73
	v_cvt_pk_bf16_f32 v181, v74, v75
	v_cvt_pk_bf16_f32 v182, v76, v77
	v_cvt_pk_bf16_f32 v183, v78, v79
	v_add_f32_e32 v174, v65, v174
	v_add_f32_e32 v175, v81, v175
	v_mfma_f32_32x32x16_bf16 v[32:47], v[124:127], v[100:103], v[32:47]
	v_cvt_pk_bf16_f32 v184, v80, v81
	v_cvt_pk_bf16_f32 v185, v82, v83
	v_cvt_pk_bf16_f32 v186, v84, v85
	v_cvt_pk_bf16_f32 v187, v86, v87
	v_add_f32_e32 v174, v66, v174
	v_add_f32_e32 v175, v82, v175
	v_mfma_f32_32x32x16_bf16 v[48:63], v[132:135], v[100:103], v[48:63]
	v_cvt_pk_bf16_f32 v188, v88, v89
	v_cvt_pk_bf16_f32 v189, v90, v91
	v_cvt_pk_bf16_f32 v190, v92, v93
	v_cvt_pk_bf16_f32 v191, v94, v95
	v_add_f32_e32 v174, v67, v174
	v_add_f32_e32 v175, v83, v175
	v_mfma_f32_32x32x16_bf16 v[32:47], v[136:139], v[104:107], v[32:47]
	v_add_f32_e32 v174, v68, v174
	v_add_f32_e32 v175, v84, v175
	v_add_f32_e32 v174, v69, v174
	v_add_f32_e32 v175, v85, v175
	v_add_f32_e32 v174, v70, v174
	v_add_f32_e32 v175, v86, v175
	v_mfma_f32_32x32x16_bf16 v[48:63], v[144:147], v[104:107], v[48:63]
	v_add_f32_e32 v174, v71, v174
	v_add_f32_e32 v175, v87, v175
	v_add_f32_e32 v174, v72, v174
	v_add_f32_e32 v175, v88, v175
	v_add_f32_e32 v174, v73, v174
	v_add_f32_e32 v175, v89, v175
	v_mfma_f32_32x32x16_bf16 v[32:47], v[140:143], v[108:111], v[32:47]
	v_add_f32_e32 v174, v74, v174
	v_add_f32_e32 v175, v90, v175
	v_add_f32_e32 v174, v75, v174
	v_add_f32_e32 v175, v91, v175
	v_add_f32_e32 v174, v76, v174
	v_add_f32_e32 v175, v92, v175
	v_mfma_f32_32x32x16_bf16 v[48:63], v[148:151], v[108:111], v[48:63]
	v_add_f32_e32 v174, v77, v174
	v_add_f32_e32 v175, v93, v175
	v_add_f32_e32 v174, v78, v174
	v_add_f32_e32 v175, v94, v175
	v_add_f32_e32 v174, v79, v174
	v_add_f32_e32 v175, v95, v175
	ds_read_b128 v[120:123], v196 offset:9280
	ds_read_b128 v[124:127], v196 offset:13888
	ds_read_b128 v[128:131], v196 offset:9312
	ds_read_b128 v[132:135], v196 offset:13920
	s_andn2_b64 vcc, exec, s[38:39]
	s_cbranch_vccnz .LBB0_832
	s_nop 3
	v_sub_f32_e32 v47, v47, v200
	v_sub_f32_e32 v46, v46, v200
	v_sub_f32_e32 v45, v45, v200
	v_sub_f32_e32 v44, v44, v200
	v_sub_f32_e32 v43, v43, v200
	v_sub_f32_e32 v42, v42, v200
	v_sub_f32_e32 v41, v41, v200
	v_sub_f32_e32 v40, v40, v200
	v_sub_f32_e32 v39, v39, v200
	v_sub_f32_e32 v38, v38, v200
	v_sub_f32_e32 v37, v37, v200
	v_sub_f32_e32 v36, v36, v200
	v_sub_f32_e32 v35, v35, v200
	v_sub_f32_e32 v34, v34, v200
	v_sub_f32_e32 v33, v33, v200
	v_sub_f32_e32 v32, v32, v200
	v_sub_f32_e32 v63, v63, v200
	v_sub_f32_e32 v62, v62, v200
	v_sub_f32_e32 v61, v61, v200
	v_sub_f32_e32 v60, v60, v200
	v_sub_f32_e32 v59, v59, v200
	v_sub_f32_e32 v58, v58, v200
	v_sub_f32_e32 v57, v57, v200
	v_sub_f32_e32 v56, v56, v200
	v_sub_f32_e32 v55, v55, v200
	v_sub_f32_e32 v54, v54, v200
	v_sub_f32_e32 v53, v53, v200
	v_sub_f32_e32 v52, v52, v200
	v_sub_f32_e32 v51, v51, v200
	v_sub_f32_e32 v50, v50, v200
	v_sub_f32_e32 v49, v49, v200
	v_sub_f32_e32 v48, v48, v200
